# diff-attention loop: waves 4-7 take the half-step barrier after their first five PV MFMAs (half a step behind waves 0-3) so SIMD partner waves no longer run in lockstep
# baseline (speedup 1.0000x reference)
; #define ATT_LAS __attribute__((address_space(3)))
; #define SB0() __builtin_amdgcn_sched_barrier(0)
; __device__ __forceinline__ void hs_fast(f32x16& S, f32x16 (&O)[4], bf16x8 (&pf)[2], float& lsum, const bf16x8 (&qf)[4], const ATT_LAS unsigned char* ka, const ATT_LAS unsigned char* va) {
;     bf16x8 kf[4], vf[8]; f32x16 N; float acc;
;     const f32x16 Z = {0.f, 0.f, 0.f, 0.f, 0.f, 0.f, 0.f, 0.f, 0.f, 0.f, 0.f, 0.f, 0.f, 0.f, 0.f, 0.f};
;     kf[0] = LDF(ka); kf[1] = LDF(ka + 32); kf[2] = LDF(ka + 64); kf[3] = LDF(ka + 96);
;     vf[0] = LDF(va); vf[1] = LDF(va + 32 * VPITCH); vf[2] = LDF(va + 64 * VPITCH); vf[3] = LDF(va + 96 * VPITCH);
;     SB0();
;     N = MFMA32(kf[0], qf[0], Z);          S[0] = EX2(S[0]); S[1] = EX2(S[1]);
;     SB0();
;     O[0] = MFMA32(vf[0], pf[0], O[0]);    S[2] = EX2(S[2]); S[3] = EX2(S[3]); acc = S[0] + S[1];
;     SB0();
;     N = MFMA32(kf[1], qf[1], N);          S[4] = EX2(S[4]); S[5] = EX2(S[5]); acc += S[2]; acc += S[3];
;     SB0();
;     O[1] = MFMA32(vf[1], pf[0], O[1]);    S[6] = EX2(S[6]); S[7] = EX2(S[7]); acc += S[4]; acc += S[5];
;     SB0();
;     N = MFMA32(kf[2], qf[2], N);          S[8] = EX2(S[8]); S[9] = EX2(S[9]); acc += S[6]; acc += S[7];
;     vf[4] = LDF(va + 32); vf[5] = LDF(va + 32 * VPITCH + 32);
;     SB0();
;     O[2] = MFMA32(vf[2], pf[0], O[2]);    S[10] = EX2(S[10]); S[11] = EX2(S[11]); acc += S[8]; acc += S[9];
;     vf[6] = LDF(va + 64 * VPITCH + 32); vf[7] = LDF(va + 96 * VPITCH + 32);
;     SB0();
;     N = MFMA32(kf[3], qf[3], N);          S[12] = EX2(S[12]); S[13] = EX2(S[13]); acc += S[10]; acc += S[11];
;     SB0();
;     O[3] = MFMA32(vf[3], pf[0], O[3]);    S[14] = EX2(S[14]); S[15] = EX2(S[15]); acc += S[12]; acc += S[13];
;     SB0();
;     u32x4 w0, w1;
;     O[0] = MFMA32(vf[4], pf[1], O[0]);    w0.x = cvt_pk_bf16(S[0], S[1]); w0.y = cvt_pk_bf16(S[2], S[3]); acc += S[14]; acc += S[15];
;     SB0();
;     O[1] = MFMA32(vf[5], pf[1], O[1]);    w0.z = cvt_pk_bf16(S[4], S[5]); w0.w = cvt_pk_bf16(S[6], S[7]);
;     SB0();
;     O[2] = MFMA32(vf[6], pf[1], O[2]);    w1.x = cvt_pk_bf16(S[8], S[9]); w1.y = cvt_pk_bf16(S[10], S[11]);
;     SB0();
;     O[3] = MFMA32(vf[7], pf[1], O[3]);    w1.z = cvt_pk_bf16(S[12], S[13]); w1.w = cvt_pk_bf16(S[14], S[15]);
;     SB0();
;     lsum += acc; pf[0] = __builtin_bit_cast(bf16x8, w0); pf[1] = __builtin_bit_cast(bf16x8, w1); S = N;
; }
.Lfa_even:
	v_mov_b32_e32 v15, v1
	v_add_u32_e32 v1, s99, v196
	s_waitcnt lgkmcnt(9)
	v_mfma_f32_32x32x16_bf16 v[96:111], v[218:221], v[112:115], 0
	v_exp_f32_e32 v80, v80
	v_exp_f32_e32 v81, v81
	ds_read_b128 v[218:221], v14 offset:8800
	v_add_f32_e32 v244, v80, v81
	s_waitcnt lgkmcnt(8)
	v_mfma_f32_32x32x16_bf16 v[64:79], v[222:225], v[144:147], v[64:79]
	v_exp_f32_e32 v82, v82
	v_exp_f32_e32 v83, v83
	ds_read_b128 v[222:225], v15 offset:31296
	v_add_f32_e32 v245, v82, v83
	s_waitcnt lgkmcnt(7)
	v_mfma_f32_32x32x16_bf16 v[96:111], v[226:229], v[116:119], v[96:111]
	v_exp_f32_e32 v84, v84
	v_exp_f32_e32 v85, v85
	ds_read_b128 v[226:229], v15 offset:17504
	v_add_f32_e32 v244, v244, v84
	v_add_f32_e32 v245, v245, v85
	s_waitcnt lgkmcnt(6)
	v_mfma_f32_32x32x16_bf16 v[48:63], v[230:233], v[144:147], v[48:63]
	v_exp_f32_e32 v86, v86
	v_exp_f32_e32 v87, v87
	ds_read_b128 v[230:233], v15 offset:22112
	v_add_f32_e32 v244, v244, v86
	v_add_f32_e32 v245, v245, v87
	s_waitcnt lgkmcnt(5)
	v_mfma_f32_32x32x16_bf16 v[96:111], v[234:237], v[120:123], v[96:111]
	v_exp_f32_e32 v88, v88
	v_exp_f32_e32 v89, v89
	ds_read_b128 v[234:237], v15 offset:26720
	v_add_f32_e32 v244, v244, v88
	v_add_f32_e32 v245, v245, v89
	s_waitcnt lgkmcnt(5)
	v_mfma_f32_32x32x16_bf16 v[32:47], v[2:5], v[144:147], v[32:47]
	v_exp_f32_e32 v90, v90
	v_exp_f32_e32 v91, v91
	ds_read_b128 v[2:5], v15 offset:31328
	v_add_f32_e32 v244, v244, v90
	v_add_f32_e32 v245, v245, v91
	s_waitcnt lgkmcnt(5)
	v_mfma_f32_32x32x16_bf16 v[96:111], v[218:221], v[124:127], v[96:111]
	v_exp_f32_e32 v92, v92
	v_exp_f32_e32 v93, v93
	ds_read_b128 v[218:221], v1 offset:17408
	v_add_f32_e32 v244, v244, v92
	v_add_f32_e32 v245, v245, v93
	s_waitcnt lgkmcnt(5)
	v_mfma_f32_32x32x16_bf16 v[16:31], v[222:225], v[144:147], v[16:31]
	v_exp_f32_e32 v94, v94
	v_exp_f32_e32 v95, v95
	ds_read_b128 v[222:225], v1 offset:22016
	v_add_f32_e32 v244, v244, v94
	v_add_f32_e32 v245, v245, v95
	s_waitcnt lgkmcnt(5)
	v_mfma_f32_32x32x16_bf16 v[64:79], v[226:229], v[150:153], v[64:79]
	v_add_f32_e32 v161, v161, v244
	v_cvt_pk_bf16_f32 v6, v80, v81
	v_cvt_pk_bf16_f32 v7, v82, v83
	ds_read_b128 v[226:229], v1 offset:26624
	s_waitcnt lgkmcnt(5)
	v_mfma_f32_32x32x16_bf16 v[48:63], v[230:233], v[150:153], v[48:63]
	v_add_f32_e32 v161, v161, v245
	v_cvt_pk_bf16_f32 v8, v84, v85
	v_cvt_pk_bf16_f32 v9, v86, v87
	ds_read_b128 v[230:233], v1 offset:31232
	s_waitcnt lgkmcnt(5)
	v_mfma_f32_32x32x16_bf16 v[32:47], v[234:237], v[150:153], v[32:47]
	v_cvt_pk_bf16_f32 v10, v88, v89
	v_cvt_pk_bf16_f32 v11, v90, v91
	s_waitcnt lgkmcnt(4)
	v_mfma_f32_32x32x16_bf16 v[16:31], v[2:5], v[150:153], v[16:31]
	v_cvt_pk_bf16_f32 v12, v92, v93
	v_cvt_pk_bf16_f32 v13, v94, v95
	ds_read_b128 v[2:5], v1 offset:17440
	s_add_i32 s46, s46, 1
	s_cmp_eq_u32 s46, s24
	s_cbranch_scc1 .Lfa_exit_even
	s_cmp_eq_u32 s41, 0
	s_cbranch_scc0 .Lfa_odd_b
	s_barrier
	v_add_u32_e32 v14, s100, v163
	ds_read_b128 v[234:237], v14
	v_add_u32_e32 v246, s98, v193
	v_add_u32_e32 v247, s98, v194
	s_waitcnt lgkmcnt(5)
	v_mfma_f32_32x32x16_bf16 v[64:79], v[218:221], v[6:9], v[64:79]
	v_exp_f32_e32 v96, v96
	v_exp_f32_e32 v97, v97
	ds_read_b128 v[218:221], v14 offset:32
	v_add_f32_e32 v244, v96, v97
	s_waitcnt lgkmcnt(5)
	v_mfma_f32_32x32x16_bf16 v[48:63], v[222:225], v[6:9], v[48:63]
	v_exp_f32_e32 v98, v98
	v_exp_f32_e32 v99, v99
	ds_read_b128 v[222:225], v1 offset:22048
	v_add_f32_e32 v245, v98, v99
	s_waitcnt lgkmcnt(5)
	v_mfma_f32_32x32x16_bf16 v[32:47], v[226:229], v[6:9], v[32:47]
	v_exp_f32_e32 v100, v100
	v_exp_f32_e32 v101, v101
	ds_read_b128 v[226:229], v14 offset:64
	v_add_f32_e32 v244, v244, v100
	v_add_f32_e32 v245, v245, v101
	s_waitcnt lgkmcnt(5)
	v_mfma_f32_32x32x16_bf16 v[16:31], v[230:233], v[6:9], v[16:31]
	v_exp_f32_e32 v102, v102
	v_exp_f32_e32 v103, v103
	ds_read_b128 v[230:233], v1 offset:26656
	v_add_f32_e32 v244, v244, v102
	v_add_f32_e32 v245, v245, v103
	s_waitcnt lgkmcnt(4)
	v_mfma_f32_32x32x16_bf16 v[80:95], v[234:237], v[112:115], 0
	v_exp_f32_e32 v104, v104
	v_exp_f32_e32 v105, v105
	ds_read_b128 v[234:237], v14 offset:96
	v_add_f32_e32 v244, v244, v104
	v_add_f32_e32 v245, v245, v105
	s_waitcnt lgkmcnt(5)
	v_mfma_f32_32x32x16_bf16 v[64:79], v[2:5], v[10:13], v[64:79]
	v_exp_f32_e32 v106, v106
	v_exp_f32_e32 v107, v107
	ds_read_b128 v[2:5], v1 offset:31264
	v_add_f32_e32 v244, v244, v106
	v_add_f32_e32 v245, v245, v107
	s_waitcnt lgkmcnt(5)
	v_mfma_f32_32x32x16_bf16 v[80:95], v[218:221], v[116:119], v[80:95]
	v_exp_f32_e32 v108, v108
	v_exp_f32_e32 v109, v109
	ds_read_b128 v[218:221], v14 offset:8704
	v_add_f32_e32 v244, v244, v108
	v_add_f32_e32 v245, v245, v109
	s_waitcnt vmcnt(0)
	ds_write_b128 v246, v[128:131]
	s_waitcnt lgkmcnt(6)
	v_mfma_f32_32x32x16_bf16 v[48:63], v[222:225], v[10:13], v[48:63]
	v_exp_f32_e32 v110, v110
	v_exp_f32_e32 v111, v111
	ds_read_b128 v[222:225], v1 offset:17472
	v_add_f32_e32 v244, v244, v110
	v_add_f32_e32 v245, v245, v111
	ds_write_b128 v247, v[132:135] offset:17408
	s_waitcnt lgkmcnt(7)
	v_mfma_f32_32x32x16_bf16 v[80:95], v[226:229], v[120:123], v[80:95]
	v_add_f32_e32 v161, v161, v244
	v_cvt_pk_bf16_f32 v144, v96, v97
	v_cvt_pk_bf16_f32 v145, v98, v99
	ds_read_b128 v[226:229], v14 offset:8736
	ds_write_b128 v246, v[136:139] offset:8704
	s_waitcnt lgkmcnt(8)
	v_mfma_f32_32x32x16_bf16 v[32:47], v[230:233], v[10:13], v[32:47]
	v_add_f32_e32 v161, v161, v245
	v_cvt_pk_bf16_f32 v146, v100, v101
	v_cvt_pk_bf16_f32 v147, v102, v103
	ds_read_b128 v[230:233], v1 offset:22080
	ds_write_b128 v247, v[140:143] offset:26624
	s_waitcnt lgkmcnt(9)
	v_mfma_f32_32x32x16_bf16 v[80:95], v[234:237], v[124:127], v[80:95]
	v_cvt_pk_bf16_f32 v150, v104, v105
	v_cvt_pk_bf16_f32 v151, v106, v107
	ds_read_b128 v[234:237], v14 offset:8768
	s_cmp_ge_u32 s47, s23
	s_cbranch_scc1 .Lfa_noload
	s_lshl_b32 s48, s47, 17
	s_mov_b32 s49, 0
	v_lshl_add_u64 v[240:241], v[182:183], 0, s[48:49]
	s_lshl_b32 s4, s47, 7
	s_add_u32 s48, s48, 0x10000
	global_load_dwordx4 v[128:131], v[240:241], off
	v_lshl_add_u64 v[242:243], v[182:183], 0, s[48:49]
	s_mov_b32 s48, s4
	v_lshl_add_u64 v[240:241], v[184:185], 0, s[48:49]
	s_add_u32 s48, s48, 0x208000
	global_load_dwordx4 v[132:135], v[240:241], off
	global_load_dwordx4 v[136:139], v[242:243], off
	v_lshl_add_u64 v[240:241], v[184:185], 0, s[48:49]
	s_nop 0
	global_load_dwordx4 v[140:143], v[240:241], off
; #define ATT_LAS __attribute__((address_space(3)))
; #define SB0() __builtin_amdgcn_sched_barrier(0)
; __device__ __forceinline__ void hs_fast(f32x16& S, f32x16 (&O)[4], bf16x8 (&pf)[2], float& lsum, const bf16x8 (&qf)[4], const ATT_LAS unsigned char* ka, const ATT_LAS unsigned char* va) {
;     bf16x8 kf[4], vf[8]; f32x16 N; float acc;
;     const f32x16 Z = {0.f, 0.f, 0.f, 0.f, 0.f, 0.f, 0.f, 0.f, 0.f, 0.f, 0.f, 0.f, 0.f, 0.f, 0.f, 0.f};
;     kf[0] = LDF(ka); kf[1] = LDF(ka + 32); kf[2] = LDF(ka + 64); kf[3] = LDF(ka + 96);
;     vf[0] = LDF(va); vf[1] = LDF(va + 32 * VPITCH); vf[2] = LDF(va + 64 * VPITCH); vf[3] = LDF(va + 96 * VPITCH);
;     SB0();
;     N = MFMA32(kf[0], qf[0], Z);          S[0] = EX2(S[0]); S[1] = EX2(S[1]);
;     SB0();
;     O[0] = MFMA32(vf[0], pf[0], O[0]);    S[2] = EX2(S[2]); S[3] = EX2(S[3]); acc = S[0] + S[1];
;     SB0();
;     N = MFMA32(kf[1], qf[1], N);          S[4] = EX2(S[4]); S[5] = EX2(S[5]); acc += S[2]; acc += S[3];
;     SB0();
;     O[1] = MFMA32(vf[1], pf[0], O[1]);    S[6] = EX2(S[6]); S[7] = EX2(S[7]); acc += S[4]; acc += S[5];
;     SB0();
;     N = MFMA32(kf[2], qf[2], N);          S[8] = EX2(S[8]); S[9] = EX2(S[9]); acc += S[6]; acc += S[7];
;     vf[4] = LDF(va + 32); vf[5] = LDF(va + 32 * VPITCH + 32);
;     SB0();
;     O[2] = MFMA32(vf[2], pf[0], O[2]);    S[10] = EX2(S[10]); S[11] = EX2(S[11]); acc += S[8]; acc += S[9];
;     vf[6] = LDF(va + 64 * VPITCH + 32); vf[7] = LDF(va + 96 * VPITCH + 32);
;     SB0();
;     N = MFMA32(kf[3], qf[3], N);          S[12] = EX2(S[12]); S[13] = EX2(S[13]); acc += S[10]; acc += S[11];
;     SB0();
;     O[3] = MFMA32(vf[3], pf[0], O[3]);    S[14] = EX2(S[14]); S[15] = EX2(S[15]); acc += S[12]; acc += S[13];
;     SB0();
;     u32x4 w0, w1;
;     O[0] = MFMA32(vf[4], pf[1], O[0]);    w0.x = cvt_pk_bf16(S[0], S[1]); w0.y = cvt_pk_bf16(S[2], S[3]); acc += S[14]; acc += S[15];
;     SB0();
;     O[1] = MFMA32(vf[5], pf[1], O[1]);    w0.z = cvt_pk_bf16(S[4], S[5]); w0.w = cvt_pk_bf16(S[6], S[7]);
;     SB0();
;     O[2] = MFMA32(vf[6], pf[1], O[2]);    w1.x = cvt_pk_bf16(S[8], S[9]); w1.y = cvt_pk_bf16(S[10], S[11]);
;     SB0();
;     O[3] = MFMA32(vf[7], pf[1], O[3]);    w1.z = cvt_pk_bf16(S[12], S[13]); w1.w = cvt_pk_bf16(S[14], S[15]);
;     SB0();
;     lsum += acc; pf[0] = __builtin_bit_cast(bf16x8, w0); pf[1] = __builtin_bit_cast(bf16x8, w1); S = N;
; }
.Lfa_noload:
	s_waitcnt lgkmcnt(9)
	v_mfma_f32_32x32x16_bf16 v[16:31], v[2:5], v[10:13], v[16:31]
	v_cvt_pk_bf16_f32 v152, v108, v109
	v_cvt_pk_bf16_f32 v153, v110, v111
	ds_read_b128 v[2:5], v1 offset:26688
	s_branch .Lfa_odd_join
.Lfa_odd_b:
	s_waitcnt lgkmcnt(4)
	v_mfma_f32_32x32x16_bf16 v[64:79], v[218:221], v[6:9], v[64:79]
	v_exp_f32_e32 v96, v96
	v_exp_f32_e32 v97, v97
	ds_read_b128 v[218:221], v1 offset:22048
	v_add_f32_e32 v244, v96, v97
	s_waitcnt lgkmcnt(4)
	v_mfma_f32_32x32x16_bf16 v[48:63], v[222:225], v[6:9], v[48:63]
	v_exp_f32_e32 v98, v98
	v_exp_f32_e32 v99, v99
	ds_read_b128 v[222:225], v1 offset:26656
	v_add_f32_e32 v245, v98, v99
	s_waitcnt lgkmcnt(4)
	v_mfma_f32_32x32x16_bf16 v[32:47], v[226:229], v[6:9], v[32:47]
	v_exp_f32_e32 v100, v100
	v_exp_f32_e32 v101, v101
	ds_read_b128 v[226:229], v1 offset:31264
	v_add_f32_e32 v244, v244, v100
	v_add_f32_e32 v245, v245, v101
	s_waitcnt lgkmcnt(4)
	v_mfma_f32_32x32x16_bf16 v[16:31], v[230:233], v[6:9], v[16:31]
	v_exp_f32_e32 v102, v102
	v_exp_f32_e32 v103, v103
	v_add_f32_e32 v244, v244, v102
	v_add_f32_e32 v245, v245, v103
	s_waitcnt lgkmcnt(3)
	v_mfma_f32_32x32x16_bf16 v[64:79], v[2:5], v[10:13], v[64:79]
	v_exp_f32_e32 v104, v104
	v_exp_f32_e32 v105, v105
	v_add_f32_e32 v244, v244, v104
	v_add_f32_e32 v245, v245, v105
	s_barrier
	v_add_u32_e32 v14, s100, v163
	ds_read_b128 v[230:233], v14
	ds_read_b128 v[234:237], v14 offset:32
	ds_read_b128 v[2:5], v14 offset:64
	ds_read_b128 v[248:251], v14 offset:96
	v_add_u32_e32 v246, s98, v193
	v_add_u32_e32 v247, s98, v194
	s_waitcnt lgkmcnt(6)
	v_mfma_f32_32x32x16_bf16 v[48:63], v[218:221], v[10:13], v[48:63]
	v_exp_f32_e32 v106, v106
	v_exp_f32_e32 v107, v107
	ds_read_b128 v[218:221], v14 offset:8704
	v_add_f32_e32 v244, v244, v106
	v_add_f32_e32 v245, v245, v107
	s_waitcnt lgkmcnt(6)
	v_mfma_f32_32x32x16_bf16 v[32:47], v[222:225], v[10:13], v[32:47]
	v_exp_f32_e32 v108, v108
	v_exp_f32_e32 v109, v109
	ds_read_b128 v[222:225], v1 offset:17472
	v_add_f32_e32 v244, v244, v108
	v_add_f32_e32 v245, v245, v109
	s_waitcnt lgkmcnt(6)
	v_mfma_f32_32x32x16_bf16 v[16:31], v[226:229], v[10:13], v[16:31]
	v_exp_f32_e32 v110, v110
	v_exp_f32_e32 v111, v111
	ds_read_b128 v[226:229], v14 offset:8736
	v_add_f32_e32 v244, v244, v110
	v_add_f32_e32 v245, v245, v111
	s_waitcnt vmcnt(0)
	ds_write_b128 v246, v[128:131]
	s_waitcnt lgkmcnt(7)
	v_mfma_f32_32x32x16_bf16 v[80:95], v[230:233], v[112:115], 0
	v_add_f32_e32 v161, v161, v244
	v_cvt_pk_bf16_f32 v144, v96, v97
	v_cvt_pk_bf16_f32 v145, v98, v99
	ds_read_b128 v[230:233], v1 offset:22080
	ds_write_b128 v247, v[132:135] offset:17408
	s_waitcnt lgkmcnt(8)
	v_mfma_f32_32x32x16_bf16 v[80:95], v[234:237], v[116:119], v[80:95]
	v_add_f32_e32 v161, v161, v245
	v_cvt_pk_bf16_f32 v146, v100, v101
	v_cvt_pk_bf16_f32 v147, v102, v103
	ds_read_b128 v[234:237], v14 offset:8768
	ds_write_b128 v246, v[136:139] offset:8704
	s_waitcnt lgkmcnt(9)
	v_mfma_f32_32x32x16_bf16 v[80:95], v[2:5], v[120:123], v[80:95]
	v_cvt_pk_bf16_f32 v150, v104, v105
	v_cvt_pk_bf16_f32 v151, v106, v107
	ds_read_b128 v[2:5], v1 offset:26688
	ds_write_b128 v247, v[140:143] offset:26624
	s_waitcnt lgkmcnt(10)
	v_mfma_f32_32x32x16_bf16 v[80:95], v[248:251], v[124:127], v[80:95]
	v_cvt_pk_bf16_f32 v152, v108, v109
	v_cvt_pk_bf16_f32 v153, v110, v111
	s_cmp_ge_u32 s47, s23
	s_cbranch_scc1 .Lfa_noload_b
	s_lshl_b32 s48, s47, 17
	s_mov_b32 s49, 0
	v_lshl_add_u64 v[240:241], v[182:183], 0, s[48:49]
	s_lshl_b32 s4, s47, 7
	s_add_u32 s48, s48, 0x10000
	global_load_dwordx4 v[128:131], v[240:241], off
	v_lshl_add_u64 v[242:243], v[182:183], 0, s[48:49]
	s_mov_b32 s48, s4
	v_lshl_add_u64 v[240:241], v[184:185], 0, s[48:49]
	s_add_u32 s48, s48, 0x208000
	global_load_dwordx4 v[132:135], v[240:241], off
	global_load_dwordx4 v[136:139], v[242:243], off
	v_lshl_add_u64 v[240:241], v[184:185], 0, s[48:49]
	s_nop 0
	global_load_dwordx4 v[140:143], v[240:241], off
.Lfa_noload_b:
.Lfa_odd_join:
	s_mov_b32 s101, s98
	s_mov_b32 s98, s99
	s_mov_b32 s99, s100
	s_mov_b32 s100, s101
	s_add_i32 s47, s47, 1
	s_add_i32 s46, s46, 1
	s_cmp_eq_u32 s46, s24
	s_cbranch_scc0 .Lfa_even
	s_waitcnt lgkmcnt(0)
	v_mov_b32_e32 v148, v150
	v_mov_b32_e32 v149, v151
	s_mov_b32 s4, s42
	s_lshl_b32 s24, s23, 1
	s_cmp_gt_u32 s4, s24
	s_cbranch_scc1 .LBB0_556
	s_branch .LBB0_544

; __global__ void __launch_bounds__(NWAVES * 64, 2) fwd(Params P) {
	.amdhsa_kernel _Z3fwd6Params
		.amdhsa_group_segment_fixed_size 0
		.amdhsa_private_segment_fixed_size 0
		.amdhsa_kernarg_size 536
		.amdhsa_user_sgpr_count 2
		.amdhsa_user_sgpr_dispatch_ptr 0
		.amdhsa_user_sgpr_queue_ptr 0
		.amdhsa_user_sgpr_kernarg_segment_ptr 1
		.amdhsa_user_sgpr_dispatch_id 0
		.amdhsa_user_sgpr_kernarg_preload_length 0
		.amdhsa_user_sgpr_kernarg_preload_offset 0
		.amdhsa_user_sgpr_private_segment_size 0
		.amdhsa_uses_dynamic_stack 0
		.amdhsa_enable_private_segment 0
		.amdhsa_system_sgpr_workgroup_id_x 1
		.amdhsa_system_sgpr_workgroup_id_y 0
		.amdhsa_system_sgpr_workgroup_id_z 0
		.amdhsa_system_sgpr_workgroup_info 0
		.amdhsa_system_vgpr_workitem_id 2
		.amdhsa_next_free_vgpr 256
		.amdhsa_next_free_sgpr 102
		.amdhsa_accum_offset 256
		.amdhsa_reserve_vcc 1
		.amdhsa_float_round_mode_32 0
		.amdhsa_float_round_mode_16_64 0
		.amdhsa_float_denorm_mode_32 3
		.amdhsa_float_denorm_mode_16_64 3
		.amdhsa_dx10_clamp 1
		.amdhsa_ieee_mode 1
		.amdhsa_fp16_overflow 0
		.amdhsa_tg_split 0
		.amdhsa_exception_fp_ieee_invalid_op 0
		.amdhsa_exception_fp_denorm_src 0
		.amdhsa_exception_fp_ieee_div_zero 0
		.amdhsa_exception_fp_ieee_overflow 0
		.amdhsa_exception_fp_ieee_underflow 0
		.amdhsa_exception_fp_ieee_inexact 0
		.amdhsa_exception_int_div_zero 0
	.end_amdhsa_kernel

; __global__ void __launch_bounds__(NWAVES * 64, 2) fwd(Params P) {
amdhsa.kernels:
  - .agpr_count:     0
    .args:
      - .offset:         0
        .size:           280
        .value_kind:     by_value
      - .offset:         280
        .size:           4
        .value_kind:     hidden_block_count_x
      - .offset:         284
        .size:           4
        .value_kind:     hidden_block_count_y
      - .offset:         288
        .size:           4
        .value_kind:     hidden_block_count_z
      - .offset:         292
        .size:           2
        .value_kind:     hidden_group_size_x
      - .offset:         294
        .size:           2
        .value_kind:     hidden_group_size_y
      - .offset:         296
        .size:           2
        .value_kind:     hidden_group_size_z
      - .offset:         298
        .size:           2
        .value_kind:     hidden_remainder_x
      - .offset:         300
        .size:           2
        .value_kind:     hidden_remainder_y
      - .offset:         302
        .size:           2
        .value_kind:     hidden_remainder_z
      - .offset:         320
        .size:           8
        .value_kind:     hidden_global_offset_x
      - .offset:         328
        .size:           8
        .value_kind:     hidden_global_offset_y
      - .offset:         336
        .size:           8
        .value_kind:     hidden_global_offset_z
      - .offset:         344
        .size:           2
        .value_kind:     hidden_grid_dims
      - .offset:         368
        .size:           8
        .value_kind:     hidden_multigrid_sync_arg
      - .offset:         400
        .size:           4
        .value_kind:     hidden_dynamic_lds_size
    .group_segment_fixed_size: 0
    .kernarg_segment_align: 8
    .kernarg_segment_size: 536
    .language:       OpenCL C
    .language_version:
      - 2
      - 0
    .max_flat_workgroup_size: 512
    .name:           _Z3fwd6Params
    .private_segment_fixed_size: 0
    .sgpr_count:     108
    .sgpr_spill_count: 28
    .symbol:         _Z3fwd6Params.kd
    .uniform_work_group_size: 1
    .uses_dynamic_stack: false
    .vgpr_count:     256
    .vgpr_spill_count: 0
    .wavefront_size: 64
